# v82 + sc1 (write-through) on the P10 AFFN epilogue stores instead of nt
# baseline (speedup 1.0000x reference)
.LBB0_1297:
	s_lshr_b32 s17, s4, 5
	s_mul_i32 s20, s17, 0x1600
	s_ashr_i32 s21, s20, 31
	s_lshl_b64 s[20:21], s[20:21], 2
	s_add_u32 s17, s46, s20
	s_addc_u32 s19, s47, s21
	s_lshl_b32 s20, s52, 8
	s_ashr_i32 s21, s20, 31
	s_lshl_b64 s[20:21], s[20:21], 2
	s_add_u32 s17, s17, s20
	s_addc_u32 s19, s19, s21
	s_lshl_b32 s20, s54, 2
	v_lshl_add_u32 v166, s4, 8, v1
	s_add_u32 s20, s17, s20
	v_ashrrev_i32_e32 v167, 31, v166
	s_addc_u32 s21, s19, 0
	v_lshlrev_b32_e32 v78, 2, v156
	v_lshl_add_u64 v[174:175], v[166:167], 2, s[10:11]
	v_add_u32_e32 v174, 0x80, v166
	v_ashrrev_i32_e32 v175, 31, v174
	v_lshl_add_u64 v[178:179], v[174:175], 2, s[10:11]
	s_lshl_b32 s20, s52, 7
	s_ashr_i32 s21, s20, 31
	s_lshl_b64 s[20:21], s[20:21], 1
	s_lshl_b32 s4, s54, 1
	s_andn2_b64 vcc, exec, s[40:41]
	s_waitcnt vmcnt(0)
	v_mov_b64_e32 v[94:95], v[234:235]
	v_mov_b64_e32 v[96:97], v[236:237]
	v_mov_b64_e32 v[82:83], v[238:239]
	v_mov_b64_e32 v[84:85], v[240:241]
	v_mov_b64_e32 v[78:79], v[242:243]
	v_mov_b64_e32 v[80:81], v[244:245]
	v_mov_b64_e32 v[70:71], v[246:247]
	v_mov_b64_e32 v[72:73], v[248:249]
	v_mov_b32_e32 v154, v250
	v_mov_b32_e32 v167, v251
	v_mov_b32_e32 v168, v252
	v_mov_b32_e32 v170, v253
	v_mov_b32_e32 v172, v254
	v_mov_b32_e32 v175, v233
	v_mov_b32_e32 v181, v232
	v_mov_b32_e32 v179, v177
	v_mov_b32_e32 v177, 0x358637bd
	v_fmamk_f32 v154, v154, 0x3a800000, v177
	v_fmamk_f32 v167, v167, 0x3a800000, v177
	v_rsq_f32_e32 v182, v167
	v_fmamk_f32 v167, v168, 0x3a800000, v177
	v_rsq_f32_e32 v154, v154
	v_rsq_f32_e32 v180, v167
	v_fmamk_f32 v167, v170, 0x3a800000, v177
	v_rsq_f32_e32 v178, v167
	v_fmamk_f32 v167, v172, 0x3a800000, v177
	v_rsq_f32_e32 v176, v167
	v_fmamk_f32 v167, v175, 0x3a800000, v177
	v_rsq_f32_e32 v172, v167
	v_fmamk_f32 v167, v181, 0x3a800000, v177
	v_rsq_f32_e32 v170, v167
	v_fmamk_f32 v167, v179, 0x3a800000, v177
	s_lshr_b32 s98, s18, 5
	s_mul_i32 s98, s98, 0x1600
	s_lshl_b32 s99, s16, 8
	s_add_i32 s98, s98, s99
	s_add_i32 s98, s98, s54
	s_lshl_b32 s98, s98, 2
	s_add_u32 s98, s46, s98
	s_addc_u32 s99, s47, 0
	v_lshlrev_b32_e32 v233, 2, v156
	v_lshl_add_u32 v232, s18, 8, v1
	global_load_dwordx4 v[234:237], v233, s[98:99]
	global_load_dwordx4 v[238:241], v233, s[98:99] offset:16
	global_load_dwordx4 v[242:245], v233, s[98:99] offset:512
	global_load_dwordx4 v[246:249], v233, s[98:99] offset:528
	v_lshlrev_b32_e32 v232, 2, v232
	global_load_dword v250, v232, s[10:11]
	global_load_dword v251, v232, s[10:11] offset:64
	global_load_dword v252, v232, s[10:11] offset:128
	global_load_dword v253, v232, s[10:11] offset:192
	global_load_dword v254, v232, s[10:11] offset:512
	global_load_dword v233, v232, s[10:11] offset:576
	global_load_dword v177, v232, s[10:11] offset:704
	global_load_dword v232, v232, s[10:11] offset:640
	v_pk_fma_f32 v[142:143], v[142:143], v[154:155], v[94:95] op_sel_hi:[1,0,1]
	v_rsq_f32_e32 v168, v167
	v_mul_f32_e32 v167, 0xbfb8aa3b, v142
	v_exp_f32_e32 v167, v167
	v_pk_fma_f32 v[138:139], v[138:139], v[154:155], v[82:83] op_sel_hi:[1,0,1]
	v_pk_fma_f32 v[134:135], v[134:135], v[154:155], v[78:79] op_sel_hi:[1,0,1]
	v_pk_fma_f32 v[140:141], v[140:141], v[154:155], v[84:85] op_sel_hi:[1,0,1]
	v_add_f32_e32 v167, 1.0, v167
	v_rcp_f32_e32 v184, v167
	v_mul_f32_e32 v167, 0xbfb8aa3b, v138
	v_exp_f32_e32 v167, v167
	v_pk_fma_f32 v[130:131], v[130:131], v[154:155], v[70:71] op_sel_hi:[1,0,1]
	v_pk_fma_f32 v[144:145], v[144:145], v[154:155], v[96:97] op_sel_hi:[1,0,1]
	v_pk_fma_f32 v[136:137], v[136:137], v[154:155], v[80:81] op_sel_hi:[1,0,1]
	v_add_f32_e32 v167, 1.0, v167
	v_rcp_f32_e32 v186, v167
	v_mul_f32_e32 v167, 0xbfb8aa3b, v143
	v_exp_f32_e32 v167, v167
	v_pk_fma_f32 v[132:133], v[132:133], v[154:155], v[72:73] op_sel_hi:[1,0,1]
	v_lshlrev_b32_e32 v154, 1, v156
	v_pk_fma_f32 v[122:123], v[122:123], v[182:183], v[82:83] op_sel_hi:[1,0,1]
	v_add_f32_e32 v167, 1.0, v167
	v_rcp_f32_e32 v185, v167
	v_pk_fma_f32 v[126:127], v[126:127], v[182:183], v[94:95] op_sel_hi:[1,0,1]
	v_pk_fma_f32 v[118:119], v[118:119], v[182:183], v[78:79] op_sel_hi:[1,0,1]
	v_pk_fma_f32 v[124:125], v[124:125], v[182:183], v[84:85] op_sel_hi:[1,0,1]
	v_pk_mul_f32 v[142:143], v[142:143], v[184:185]
	v_pk_fma_f32 v[106:107], v[106:107], v[182:183], v[70:71] op_sel_hi:[1,0,1]
	v_pk_mul_f32 v[134:135], v[134:135], v[142:143]
	v_mul_f32_e32 v142, 0xbfb8aa3b, v139
	v_exp_f32_e32 v142, v142
	v_pk_fma_f32 v[128:129], v[128:129], v[182:183], v[96:97] op_sel_hi:[1,0,1]
	v_pk_fma_f32 v[120:121], v[120:121], v[182:183], v[80:81] op_sel_hi:[1,0,1]
	v_pk_fma_f32 v[108:109], v[108:109], v[182:183], v[72:73] op_sel_hi:[1,0,1]
	v_add_f32_e32 v142, 1.0, v142
	v_rcp_f32_e32 v187, v142
	v_pk_fma_f32 v[110:111], v[110:111], v[180:181], v[82:83] op_sel_hi:[1,0,1]
	v_pk_fma_f32 v[102:103], v[102:103], v[180:181], v[78:79] op_sel_hi:[1,0,1]
	v_pk_fma_f32 v[112:113], v[112:113], v[180:181], v[84:85] op_sel_hi:[1,0,1]
	v_pk_mul_f32 v[138:139], v[138:139], v[186:187]
	v_pk_fma_f32 v[86:87], v[86:87], v[180:181], v[70:71] op_sel_hi:[1,0,1]
	v_pk_mul_f32 v[138:139], v[130:131], v[138:139]
	v_mul_f32_e32 v131, 0xbfb8aa3b, v140
	v_exp_f32_e32 v131, v131
	v_mul_f32_e32 v130, 0xbfb8aa3b, v144
	v_exp_f32_e32 v130, v130
	v_pk_fma_f32 v[104:105], v[104:105], v[180:181], v[80:81] op_sel_hi:[1,0,1]
	v_add_f32_e32 v131, 1.0, v131
	v_rcp_f32_e32 v142, v131
	v_mul_f32_e32 v131, 0xbfb8aa3b, v145
	v_exp_f32_e32 v131, v131
	v_add_f32_e32 v130, 1.0, v130
	v_rcp_f32_e32 v130, v130
	v_pk_fma_f32 v[88:89], v[88:89], v[180:181], v[72:73] op_sel_hi:[1,0,1]
	v_add_f32_e32 v131, 1.0, v131
	v_rcp_f32_e32 v131, v131
	v_pk_fma_f32 v[90:91], v[90:91], v[178:179], v[82:83] op_sel_hi:[1,0,1]
	v_pk_fma_f32 v[74:75], v[74:75], v[178:179], v[78:79] op_sel_hi:[1,0,1]
	v_pk_fma_f32 v[92:93], v[92:93], v[178:179], v[84:85] op_sel_hi:[1,0,1]
	v_pk_mul_f32 v[130:131], v[144:145], v[130:131]
	v_pk_fma_f32 v[66:67], v[66:67], v[178:179], v[70:71] op_sel_hi:[1,0,1]
	v_pk_mul_f32 v[136:137], v[136:137], v[130:131]
	v_mul_f32_e32 v130, 0xbfb8aa3b, v141
	v_exp_f32_e32 v130, v130
	v_pk_fma_f32 v[76:77], v[76:77], v[178:179], v[80:81] op_sel_hi:[1,0,1]
	v_pk_fma_f32 v[68:69], v[68:69], v[178:179], v[72:73] op_sel_hi:[1,0,1]
	v_pk_fma_f32 v[58:59], v[58:59], v[176:177], v[82:83] op_sel_hi:[1,0,1]
	v_add_f32_e32 v130, 1.0, v130
	v_rcp_f32_e32 v143, v130
	v_pk_fma_f32 v[62:63], v[62:63], v[176:177], v[94:95] op_sel_hi:[1,0,1]
	v_pk_fma_f32 v[54:55], v[54:55], v[176:177], v[78:79] op_sel_hi:[1,0,1]
	v_pk_fma_f32 v[60:61], v[60:61], v[176:177], v[84:85] op_sel_hi:[1,0,1]
	v_pk_mul_f32 v[130:131], v[140:141], v[142:143]
	v_pk_fma_f32 v[42:43], v[42:43], v[176:177], v[70:71] op_sel_hi:[1,0,1]
	v_pk_mul_f32 v[140:141], v[132:133], v[130:131]
	v_cvt_pk_bf16_f32 v130, v134, v135
	v_mov_b64_e32 v[134:135], s[8:9]
	v_cvt_pk_bf16_f32 v131, v136, v137
	v_mad_i64_i32 v[136:137], s[22:23], v166, s92, v[134:135]
	v_lshl_add_u64 v[136:137], v[136:137], 0, s[20:21]
	v_lshl_add_u64 v[136:137], v[136:137], 0, s[4:5]
	v_cvt_pk_bf16_f32 v132, v138, v139
	v_cvt_pk_bf16_f32 v133, v140, v141
	v_lshl_add_u64 v[136:137], v[136:137], 0, v[154:155]
	global_store_dwordx4 v[136:137], v[130:133], off sc1
	v_pk_fma_f32 v[64:65], v[64:65], v[176:177], v[96:97] op_sel_hi:[1,0,1]
	v_pk_fma_f32 v[56:57], v[56:57], v[176:177], v[80:81] op_sel_hi:[1,0,1]
	v_mul_f32_e32 v131, 0xbfb8aa3b, v122
	v_exp_f32_e32 v131, v131
	v_mul_f32_e32 v130, 0xbfb8aa3b, v126
	v_exp_f32_e32 v130, v130
	v_pk_fma_f32 v[44:45], v[44:45], v[176:177], v[72:73] op_sel_hi:[1,0,1]
	v_add_f32_e32 v131, 1.0, v131
	v_rcp_f32_e32 v132, v131
	v_mul_f32_e32 v131, 0xbfb8aa3b, v127
	v_exp_f32_e32 v131, v131
	v_add_f32_e32 v130, 1.0, v130
	v_rcp_f32_e32 v130, v130
	v_pk_fma_f32 v[46:47], v[46:47], v[172:173], v[82:83] op_sel_hi:[1,0,1]
	v_add_f32_e32 v131, 1.0, v131
	v_rcp_f32_e32 v131, v131
	v_pk_fma_f32 v[38:39], v[38:39], v[172:173], v[78:79] op_sel_hi:[1,0,1]
	v_pk_fma_f32 v[48:49], v[48:49], v[172:173], v[84:85] op_sel_hi:[1,0,1]
	v_pk_fma_f32 v[26:27], v[26:27], v[172:173], v[70:71] op_sel_hi:[1,0,1]
	v_pk_mul_f32 v[126:127], v[126:127], v[130:131]
	v_pk_fma_f32 v[40:41], v[40:41], v[172:173], v[80:81] op_sel_hi:[1,0,1]
	v_pk_mul_f32 v[118:119], v[118:119], v[126:127]
	v_mul_f32_e32 v126, 0xbfb8aa3b, v123
	v_exp_f32_e32 v126, v126
	v_pk_fma_f32 v[28:29], v[28:29], v[172:173], v[72:73] op_sel_hi:[1,0,1]
	v_pk_fma_f32 v[30:31], v[30:31], v[170:171], v[82:83] op_sel_hi:[1,0,1]
	v_pk_fma_f32 v[22:23], v[22:23], v[170:171], v[78:79] op_sel_hi:[1,0,1]
	v_add_f32_e32 v126, 1.0, v126
	v_rcp_f32_e32 v133, v126
	v_pk_fma_f32 v[32:33], v[32:33], v[170:171], v[84:85] op_sel_hi:[1,0,1]
	v_pk_fma_f32 v[10:11], v[10:11], v[170:171], v[70:71] op_sel_hi:[1,0,1]
	v_pk_fma_f32 v[24:25], v[24:25], v[170:171], v[80:81] op_sel_hi:[1,0,1]
	v_pk_mul_f32 v[122:123], v[122:123], v[132:133]
	v_pk_fma_f32 v[12:13], v[12:13], v[170:171], v[72:73] op_sel_hi:[1,0,1]
	v_pk_mul_f32 v[122:123], v[106:107], v[122:123]
	v_mul_f32_e32 v107, 0xbfb8aa3b, v124
	v_exp_f32_e32 v107, v107
	v_mul_f32_e32 v106, 0xbfb8aa3b, v128
	v_exp_f32_e32 v106, v106
	v_pk_fma_f32 v[14:15], v[14:15], v[168:169], v[82:83] op_sel_hi:[1,0,1]
	v_add_f32_e32 v107, 1.0, v107
	v_rcp_f32_e32 v126, v107
	v_mul_f32_e32 v107, 0xbfb8aa3b, v129
	v_exp_f32_e32 v107, v107
	v_add_f32_e32 v106, 1.0, v106
	v_rcp_f32_e32 v106, v106
	v_pk_fma_f32 v[6:7], v[6:7], v[168:169], v[78:79] op_sel_hi:[1,0,1]
	v_add_f32_e32 v107, 1.0, v107
	v_rcp_f32_e32 v107, v107
	v_pk_fma_f32 v[16:17], v[16:17], v[168:169], v[84:85] op_sel_hi:[1,0,1]
	v_pk_fma_f32 v[2:3], v[2:3], v[168:169], v[70:71] op_sel_hi:[1,0,1]
	v_pk_fma_f32 v[8:9], v[8:9], v[168:169], v[80:81] op_sel_hi:[1,0,1]
	v_pk_mul_f32 v[106:107], v[128:129], v[106:107]
	v_pk_fma_f32 v[4:5], v[4:5], v[168:169], v[72:73] op_sel_hi:[1,0,1]
	v_pk_mul_f32 v[120:121], v[120:121], v[106:107]
	v_mul_f32_e32 v106, 0xbfb8aa3b, v125
	v_exp_f32_e32 v106, v106
	s_nop 0
	v_add_f32_e32 v106, 1.0, v106
	v_rcp_f32_e32 v127, v106
	s_nop 0
	v_pk_mul_f32 v[106:107], v[124:125], v[126:127]
	v_or_b32_e32 v126, 16, v166
	v_pk_mul_f32 v[124:125], v[108:109], v[106:107]
	v_cvt_pk_bf16_f32 v106, v118, v119
	v_mad_i64_i32 v[118:119], s[22:23], v126, s92, v[134:135]
	v_lshl_add_u64 v[118:119], v[118:119], 0, s[20:21]
	v_lshl_add_u64 v[118:119], v[118:119], 0, s[4:5]
	v_cvt_pk_bf16_f32 v107, v120, v121
	v_cvt_pk_bf16_f32 v108, v122, v123
	v_cvt_pk_bf16_f32 v109, v124, v125
	v_lshl_add_u64 v[118:119], v[118:119], 0, v[154:155]
	global_store_dwordx4 v[118:119], v[106:109], off sc1
	s_nop 1
	v_pk_fma_f32 v[108:109], v[114:115], v[180:181], v[94:95] op_sel_hi:[1,0,1]
	v_mul_f32_e32 v115, 0xbfb8aa3b, v110
	v_exp_f32_e32 v115, v115
	v_pk_fma_f32 v[106:107], v[116:117], v[180:181], v[96:97] op_sel_hi:[1,0,1]
	v_mul_f32_e32 v114, 0xbfb8aa3b, v108
	v_exp_f32_e32 v114, v114
	v_add_f32_e32 v115, 1.0, v115
	v_rcp_f32_e32 v116, v115
	v_mul_f32_e32 v115, 0xbfb8aa3b, v109
	v_exp_f32_e32 v115, v115
	v_add_f32_e32 v114, 1.0, v114
	v_rcp_f32_e32 v114, v114
	v_add_f32_e32 v115, 1.0, v115
	v_rcp_f32_e32 v115, v115
	s_nop 0
	v_pk_mul_f32 v[108:109], v[108:109], v[114:115]
	s_nop 0
	v_pk_mul_f32 v[102:103], v[102:103], v[108:109]
	v_mul_f32_e32 v108, 0xbfb8aa3b, v111
	v_exp_f32_e32 v108, v108
	s_nop 0
	v_add_f32_e32 v108, 1.0, v108
	v_rcp_f32_e32 v117, v108
	s_nop 0
	v_pk_mul_f32 v[108:109], v[110:111], v[116:117]
	s_nop 0
	v_pk_mul_f32 v[108:109], v[86:87], v[108:109]
	v_mul_f32_e32 v87, 0xbfb8aa3b, v112
	v_exp_f32_e32 v87, v87
	v_mul_f32_e32 v86, 0xbfb8aa3b, v106
	v_exp_f32_e32 v86, v86
	v_add_f32_e32 v87, 1.0, v87
	v_rcp_f32_e32 v110, v87
	v_mul_f32_e32 v87, 0xbfb8aa3b, v107
	v_exp_f32_e32 v87, v87
	v_add_f32_e32 v86, 1.0, v86
	v_rcp_f32_e32 v86, v86
	v_add_f32_e32 v87, 1.0, v87
	v_rcp_f32_e32 v87, v87
	s_nop 0
	v_pk_mul_f32 v[86:87], v[106:107], v[86:87]
	s_nop 0
	v_pk_mul_f32 v[104:105], v[104:105], v[86:87]
	v_mul_f32_e32 v86, 0xbfb8aa3b, v113
	v_exp_f32_e32 v86, v86
	s_nop 0
	v_add_f32_e32 v86, 1.0, v86
	v_rcp_f32_e32 v111, v86
	s_nop 0
	v_pk_mul_f32 v[86:87], v[112:113], v[110:111]
	v_or_b32_e32 v110, 32, v166
	v_pk_mul_f32 v[106:107], v[88:89], v[86:87]
	v_cvt_pk_bf16_f32 v86, v102, v103
	v_mad_i64_i32 v[102:103], s[22:23], v110, s92, v[134:135]
	v_lshl_add_u64 v[102:103], v[102:103], 0, s[20:21]
	v_lshl_add_u64 v[102:103], v[102:103], 0, s[4:5]
	v_cvt_pk_bf16_f32 v87, v104, v105
	v_cvt_pk_bf16_f32 v88, v108, v109
	v_cvt_pk_bf16_f32 v89, v106, v107
	v_lshl_add_u64 v[102:103], v[102:103], 0, v[154:155]
	global_store_dwordx4 v[102:103], v[86:89], off sc1
	s_nop 1
	v_pk_fma_f32 v[88:89], v[98:99], v[178:179], v[94:95] op_sel_hi:[1,0,1]
	v_mul_f32_e32 v99, 0xbfb8aa3b, v90
	v_exp_f32_e32 v99, v99
	v_pk_fma_f32 v[86:87], v[100:101], v[178:179], v[96:97] op_sel_hi:[1,0,1]
	v_mul_f32_e32 v98, 0xbfb8aa3b, v88
	v_exp_f32_e32 v98, v98
	v_add_f32_e32 v99, 1.0, v99
	v_rcp_f32_e32 v100, v99
	v_mul_f32_e32 v99, 0xbfb8aa3b, v89
	v_exp_f32_e32 v99, v99
	v_add_f32_e32 v98, 1.0, v98
	v_rcp_f32_e32 v98, v98
	v_add_f32_e32 v99, 1.0, v99
	v_rcp_f32_e32 v99, v99
	s_nop 0
	v_pk_mul_f32 v[88:89], v[88:89], v[98:99]
	s_nop 0
	v_pk_mul_f32 v[74:75], v[74:75], v[88:89]
	v_mul_f32_e32 v88, 0xbfb8aa3b, v91
	v_exp_f32_e32 v88, v88
	s_nop 0
	v_add_f32_e32 v88, 1.0, v88
	v_rcp_f32_e32 v101, v88
	s_nop 0
	v_pk_mul_f32 v[88:89], v[90:91], v[100:101]
	s_nop 0
	v_pk_mul_f32 v[88:89], v[66:67], v[88:89]
	v_mul_f32_e32 v67, 0xbfb8aa3b, v92
	v_exp_f32_e32 v67, v67
	v_mul_f32_e32 v66, 0xbfb8aa3b, v86
	v_exp_f32_e32 v66, v66
	v_add_f32_e32 v67, 1.0, v67
	v_rcp_f32_e32 v90, v67
	v_mul_f32_e32 v67, 0xbfb8aa3b, v87
	v_exp_f32_e32 v67, v67
	v_add_f32_e32 v66, 1.0, v66
	v_rcp_f32_e32 v66, v66
	v_add_f32_e32 v67, 1.0, v67
	v_rcp_f32_e32 v67, v67
	s_nop 0
	v_pk_mul_f32 v[66:67], v[86:87], v[66:67]
	s_nop 0
	v_pk_mul_f32 v[76:77], v[76:77], v[66:67]
	v_mul_f32_e32 v66, 0xbfb8aa3b, v93
	v_exp_f32_e32 v66, v66
	s_nop 0
	v_add_f32_e32 v66, 1.0, v66
	v_rcp_f32_e32 v91, v66
	s_nop 0
	v_pk_mul_f32 v[66:67], v[92:93], v[90:91]
	v_or_b32_e32 v90, 48, v166
	v_pk_mul_f32 v[86:87], v[68:69], v[66:67]
	v_cvt_pk_bf16_f32 v66, v74, v75
	v_mad_i64_i32 v[74:75], s[22:23], v90, s92, v[134:135]
	v_lshl_add_u64 v[74:75], v[74:75], 0, s[20:21]
	v_lshl_add_u64 v[74:75], v[74:75], 0, s[4:5]
	v_cvt_pk_bf16_f32 v67, v76, v77
	v_cvt_pk_bf16_f32 v68, v88, v89
	v_cvt_pk_bf16_f32 v69, v86, v87
	v_lshl_add_u64 v[74:75], v[74:75], 0, v[154:155]
	global_store_dwordx4 v[74:75], v[66:69], off sc1
	s_nop 1
	v_mul_f32_e32 v67, 0xbfb8aa3b, v58
	v_exp_f32_e32 v67, v67
	v_mul_f32_e32 v66, 0xbfb8aa3b, v62
	v_exp_f32_e32 v66, v66
	v_add_f32_e32 v67, 1.0, v67
	v_rcp_f32_e32 v68, v67
	v_mul_f32_e32 v67, 0xbfb8aa3b, v63
	v_exp_f32_e32 v67, v67
	v_add_f32_e32 v66, 1.0, v66
	v_rcp_f32_e32 v66, v66
	v_add_f32_e32 v67, 1.0, v67
	v_rcp_f32_e32 v67, v67
	s_nop 0
	v_pk_mul_f32 v[62:63], v[62:63], v[66:67]
	s_nop 0
	v_pk_mul_f32 v[54:55], v[54:55], v[62:63]
	v_mul_f32_e32 v62, 0xbfb8aa3b, v59
	v_exp_f32_e32 v62, v62
	s_nop 0
	v_add_f32_e32 v62, 1.0, v62
	v_rcp_f32_e32 v69, v62
	s_nop 0
	v_pk_mul_f32 v[58:59], v[58:59], v[68:69]
	s_nop 0
	v_pk_mul_f32 v[58:59], v[42:43], v[58:59]
	v_mul_f32_e32 v43, 0xbfb8aa3b, v60
	v_exp_f32_e32 v43, v43
	v_mul_f32_e32 v42, 0xbfb8aa3b, v64
	v_exp_f32_e32 v42, v42
	v_add_f32_e32 v43, 1.0, v43
	v_rcp_f32_e32 v62, v43
	v_mul_f32_e32 v43, 0xbfb8aa3b, v65
	v_exp_f32_e32 v43, v43
	v_add_f32_e32 v42, 1.0, v42
	v_rcp_f32_e32 v42, v42
	v_add_f32_e32 v43, 1.0, v43
	v_rcp_f32_e32 v43, v43
	s_nop 0
	v_pk_mul_f32 v[42:43], v[64:65], v[42:43]
	s_nop 0
	v_pk_mul_f32 v[56:57], v[56:57], v[42:43]
	v_mul_f32_e32 v42, 0xbfb8aa3b, v61
	v_exp_f32_e32 v42, v42
	s_nop 0
	v_add_f32_e32 v42, 1.0, v42
	v_rcp_f32_e32 v63, v42
	s_nop 0
	v_pk_mul_f32 v[42:43], v[60:61], v[62:63]
	s_nop 0
	v_pk_mul_f32 v[60:61], v[44:45], v[42:43]
	v_cvt_pk_bf16_f32 v42, v54, v55
	v_mad_i64_i32 v[54:55], s[22:23], v174, s92, v[134:135]
	v_lshl_add_u64 v[54:55], v[54:55], 0, s[20:21]
	v_lshl_add_u64 v[54:55], v[54:55], 0, s[4:5]
	v_cvt_pk_bf16_f32 v43, v56, v57
	v_cvt_pk_bf16_f32 v44, v58, v59
	v_cvt_pk_bf16_f32 v45, v60, v61
	v_lshl_add_u64 v[54:55], v[54:55], 0, v[154:155]
	global_store_dwordx4 v[54:55], v[42:45], off sc1
	s_nop 1
	v_pk_fma_f32 v[44:45], v[50:51], v[172:173], v[94:95] op_sel_hi:[1,0,1]
	v_mul_f32_e32 v51, 0xbfb8aa3b, v46
	v_exp_f32_e32 v51, v51
	v_pk_fma_f32 v[42:43], v[52:53], v[172:173], v[96:97] op_sel_hi:[1,0,1]
	v_mul_f32_e32 v50, 0xbfb8aa3b, v44
	v_exp_f32_e32 v50, v50
	v_add_f32_e32 v51, 1.0, v51
	v_rcp_f32_e32 v52, v51
	v_mul_f32_e32 v51, 0xbfb8aa3b, v45
	v_exp_f32_e32 v51, v51
	v_add_f32_e32 v50, 1.0, v50
	v_rcp_f32_e32 v50, v50
	v_add_f32_e32 v51, 1.0, v51
	v_rcp_f32_e32 v51, v51
	s_nop 0
	v_pk_mul_f32 v[44:45], v[44:45], v[50:51]
	s_nop 0
	v_pk_mul_f32 v[38:39], v[38:39], v[44:45]
	v_mul_f32_e32 v44, 0xbfb8aa3b, v47
	v_exp_f32_e32 v44, v44
	s_nop 0
	v_add_f32_e32 v44, 1.0, v44
	v_rcp_f32_e32 v53, v44
	s_nop 0
	v_pk_mul_f32 v[44:45], v[46:47], v[52:53]
	s_nop 0
	v_pk_mul_f32 v[44:45], v[26:27], v[44:45]
	v_mul_f32_e32 v27, 0xbfb8aa3b, v48
	v_exp_f32_e32 v27, v27
	v_mul_f32_e32 v26, 0xbfb8aa3b, v42
	v_exp_f32_e32 v26, v26
	v_add_f32_e32 v27, 1.0, v27
	v_rcp_f32_e32 v46, v27
	v_mul_f32_e32 v27, 0xbfb8aa3b, v43
	v_exp_f32_e32 v27, v27
	v_add_f32_e32 v26, 1.0, v26
	v_rcp_f32_e32 v26, v26
	v_add_f32_e32 v27, 1.0, v27
	v_rcp_f32_e32 v27, v27
	s_nop 0
	v_pk_mul_f32 v[26:27], v[42:43], v[26:27]
	s_nop 0
	v_pk_mul_f32 v[40:41], v[40:41], v[26:27]
	v_mul_f32_e32 v26, 0xbfb8aa3b, v49
	v_exp_f32_e32 v26, v26
	s_nop 0
	v_add_f32_e32 v26, 1.0, v26
	v_rcp_f32_e32 v47, v26
	s_nop 0
	v_pk_mul_f32 v[26:27], v[48:49], v[46:47]
	v_add_u32_e32 v46, 0x90, v166
	v_pk_mul_f32 v[42:43], v[28:29], v[26:27]
	v_cvt_pk_bf16_f32 v26, v38, v39
	v_mad_i64_i32 v[38:39], s[22:23], v46, s92, v[134:135]
	v_lshl_add_u64 v[38:39], v[38:39], 0, s[20:21]
	v_lshl_add_u64 v[38:39], v[38:39], 0, s[4:5]
	v_cvt_pk_bf16_f32 v27, v40, v41
	v_cvt_pk_bf16_f32 v28, v44, v45
	v_cvt_pk_bf16_f32 v29, v42, v43
	v_lshl_add_u64 v[38:39], v[38:39], 0, v[154:155]
	global_store_dwordx4 v[38:39], v[26:29], off sc1
	s_nop 1
	v_pk_fma_f32 v[28:29], v[34:35], v[170:171], v[94:95] op_sel_hi:[1,0,1]
	v_mul_f32_e32 v35, 0xbfb8aa3b, v30
	v_exp_f32_e32 v35, v35
	v_pk_fma_f32 v[26:27], v[36:37], v[170:171], v[96:97] op_sel_hi:[1,0,1]
	v_mul_f32_e32 v34, 0xbfb8aa3b, v28
	v_exp_f32_e32 v34, v34
	v_add_f32_e32 v35, 1.0, v35
	v_rcp_f32_e32 v36, v35
	v_mul_f32_e32 v35, 0xbfb8aa3b, v29
	v_exp_f32_e32 v35, v35
	v_add_f32_e32 v34, 1.0, v34
	v_rcp_f32_e32 v34, v34
	v_add_f32_e32 v35, 1.0, v35
	v_rcp_f32_e32 v35, v35
	s_nop 0
	v_pk_mul_f32 v[28:29], v[28:29], v[34:35]
	s_nop 0
	v_pk_mul_f32 v[22:23], v[22:23], v[28:29]
	v_mul_f32_e32 v28, 0xbfb8aa3b, v31
	v_exp_f32_e32 v28, v28
	s_nop 0
	v_add_f32_e32 v28, 1.0, v28
	v_rcp_f32_e32 v37, v28
	s_nop 0
	v_pk_mul_f32 v[28:29], v[30:31], v[36:37]
	s_nop 0
	v_pk_mul_f32 v[28:29], v[10:11], v[28:29]
	v_mul_f32_e32 v11, 0xbfb8aa3b, v32
	v_exp_f32_e32 v11, v11
	v_mul_f32_e32 v10, 0xbfb8aa3b, v26
	v_exp_f32_e32 v10, v10
	v_add_f32_e32 v11, 1.0, v11
	v_rcp_f32_e32 v30, v11
	v_mul_f32_e32 v11, 0xbfb8aa3b, v27
	v_exp_f32_e32 v11, v11
	v_add_f32_e32 v10, 1.0, v10
	v_rcp_f32_e32 v10, v10
	v_add_f32_e32 v11, 1.0, v11
	v_rcp_f32_e32 v11, v11
	s_nop 0
	v_pk_mul_f32 v[10:11], v[26:27], v[10:11]
	s_nop 0
	v_pk_mul_f32 v[24:25], v[24:25], v[10:11]
	v_mul_f32_e32 v10, 0xbfb8aa3b, v33
	v_exp_f32_e32 v10, v10
	s_nop 0
	v_add_f32_e32 v10, 1.0, v10
	v_rcp_f32_e32 v31, v10
	s_nop 0
	v_pk_mul_f32 v[10:11], v[32:33], v[30:31]
	v_add_u32_e32 v30, 0xa0, v166
	v_pk_mul_f32 v[26:27], v[12:13], v[10:11]
	v_cvt_pk_bf16_f32 v10, v22, v23
	v_mad_i64_i32 v[22:23], s[22:23], v30, s92, v[134:135]
	v_lshl_add_u64 v[22:23], v[22:23], 0, s[20:21]
	v_lshl_add_u64 v[22:23], v[22:23], 0, s[4:5]
	v_cvt_pk_bf16_f32 v11, v24, v25
	v_cvt_pk_bf16_f32 v12, v28, v29
	v_cvt_pk_bf16_f32 v13, v26, v27
	v_lshl_add_u64 v[22:23], v[22:23], 0, v[154:155]
	global_store_dwordx4 v[22:23], v[10:13], off sc1
	s_nop 1
	v_pk_fma_f32 v[12:13], v[18:19], v[168:169], v[94:95] op_sel_hi:[1,0,1]
	v_mul_f32_e32 v19, 0xbfb8aa3b, v14
	v_exp_f32_e32 v19, v19
	v_pk_fma_f32 v[10:11], v[20:21], v[168:169], v[96:97] op_sel_hi:[1,0,1]
	v_mul_f32_e32 v18, 0xbfb8aa3b, v12
	v_exp_f32_e32 v18, v18
	v_add_f32_e32 v19, 1.0, v19
	v_rcp_f32_e32 v20, v19
	v_mul_f32_e32 v19, 0xbfb8aa3b, v13
	v_exp_f32_e32 v19, v19
	v_add_f32_e32 v18, 1.0, v18
	v_rcp_f32_e32 v18, v18
	v_add_f32_e32 v19, 1.0, v19
	v_rcp_f32_e32 v19, v19
	s_nop 0
	v_pk_mul_f32 v[12:13], v[12:13], v[18:19]
	s_nop 0
	v_pk_mul_f32 v[6:7], v[6:7], v[12:13]
	v_mul_f32_e32 v12, 0xbfb8aa3b, v15
	v_exp_f32_e32 v12, v12
	s_nop 0
	v_add_f32_e32 v12, 1.0, v12
	v_rcp_f32_e32 v21, v12
	s_nop 0
	v_pk_mul_f32 v[12:13], v[14:15], v[20:21]
	s_nop 0
	v_pk_mul_f32 v[12:13], v[2:3], v[12:13]
	v_mul_f32_e32 v3, 0xbfb8aa3b, v16
	v_exp_f32_e32 v3, v3
	v_mul_f32_e32 v2, 0xbfb8aa3b, v10
	v_exp_f32_e32 v2, v2
	v_add_f32_e32 v3, 1.0, v3
	v_rcp_f32_e32 v14, v3
	v_mul_f32_e32 v3, 0xbfb8aa3b, v11
	v_exp_f32_e32 v3, v3
	v_add_f32_e32 v2, 1.0, v2
	v_rcp_f32_e32 v2, v2
	v_add_f32_e32 v3, 1.0, v3
	v_rcp_f32_e32 v3, v3
	s_nop 0
	v_pk_mul_f32 v[2:3], v[10:11], v[2:3]
	s_nop 0
	v_pk_mul_f32 v[8:9], v[8:9], v[2:3]
	v_mul_f32_e32 v2, 0xbfb8aa3b, v17
	v_exp_f32_e32 v2, v2
	s_nop 0
	v_add_f32_e32 v2, 1.0, v2
	v_rcp_f32_e32 v15, v2
	s_nop 0
	v_pk_mul_f32 v[2:3], v[16:17], v[14:15]
	v_add_u32_e32 v14, 0xb0, v166
	v_pk_mul_f32 v[10:11], v[4:5], v[2:3]
	v_cvt_pk_bf16_f32 v2, v6, v7
	v_mad_i64_i32 v[6:7], s[22:23], v14, s92, v[134:135]
	v_lshl_add_u64 v[6:7], v[6:7], 0, s[20:21]
	v_lshl_add_u64 v[6:7], v[6:7], 0, s[4:5]
	v_cvt_pk_bf16_f32 v3, v8, v9
	v_cvt_pk_bf16_f32 v4, v12, v13
	v_cvt_pk_bf16_f32 v5, v10, v11
	v_lshl_add_u64 v[6:7], v[6:7], 0, v[154:155]
	s_mov_b64 s[20:21], -1
	global_store_dwordx4 v[6:7], v[2:5], off sc1
	s_cbranch_vccnz .LBB0_1290
	s_andn2_b64 vcc, exec, s[6:7]
	s_cbranch_vccnz .LBB0_1289
	s_barrier
	s_branch .LBB0_1289
